# v46 + same 0.85us guard after the G1S1 grid barrier (start of the G3S3 mixer phase)
# baseline (speedup 1.0000x reference)
.LBB0_603:
	s_or_b64 exec, exec, s[0:1]
	v_readlane_b32 s0, v254, 29
	v_readlane_b32 s1, v254, 30
	s_andn2_b64 vcc, exec, s[0:1]
	s_waitcnt lgkmcnt(0)
	s_barrier
	s_sleep 32
	s_cbranch_vccnz .LBB0_605
	s_sleep 0x7f
